# v41: v37 with the barrier's L1 invalidate issued right behind the arrival atomic so that the same wait covers both (no un-waited invalidate on the releasing block)
# speedup vs baseline: 1.0294x; 1.0294x over previous
.LBB0_276:
	s_cmp_lt_i32 s59, 2
	s_barrier
	s_cbranch_scc1 .LBB0_330
	s_waitcnt vmcnt(0)
	s_barrier
	s_and_saveexec_b64 s[2:3], s[0:1]
	s_cbranch_execz .LBB0_329
	s_waitcnt vmcnt(0) lgkmcnt(0)
	v_mov_b32_e32 v241, 0
	v_lshlrev_b32_e64 v254, 8, s31
	v_mov_b32_e32 v247, 1
	v_add_u32_e32 v246, 0x1400, v254
	global_atomic_add v248, v246, v247, s[60:61] sc0
	buffer_inv sc1

.Lxb0_go:
	v_add_u32_e32 v249, 1, v244
	ds_write_b32 v241, v249 offset:8
	v_sub_u32_e32 v255, v249, v245
	v_mul_lo_u32 v250, v255, v242
	v_mul_lo_u32 v251, v255, v243
	v_add_u32_e32 v253, 0x2400, v254
	v_mov_b32_e32 v252, 0
	s_waitcnt vmcnt(0)
	v_add_u32_e32 v248, 1, v248
	v_cmp_eq_u32_e32 vcc, v248, v250
	s_cbranch_vccz .Lxb0_wait
	buffer_wbl2 sc1
	s_waitcnt vmcnt(0)
	v_mov_b32_e32 v246, 0x3400
	global_atomic_add v248, v246, v247, s[60:61] sc0
	s_waitcnt vmcnt(0)
	v_add_u32_e32 v248, 1, v248
	v_cmp_ge_u32_e32 vcc, v248, v251
	s_cbranch_vccz .Lxb0_wait
	v_mov_b32_e32 v246, 0x2400
	global_atomic_add v246, v247, s[60:61]
	global_atomic_add v246, v247, s[60:61] offset:256
	global_atomic_add v246, v247, s[60:61] offset:512
	global_atomic_add v246, v247, s[60:61] offset:768
	global_atomic_add v246, v247, s[60:61] offset:1024
	global_atomic_add v246, v247, s[60:61] offset:1280
	global_atomic_add v246, v247, s[60:61] offset:1536
	global_atomic_add v246, v247, s[60:61] offset:1792
	global_atomic_add v246, v247, s[60:61] offset:2048
	global_atomic_add v246, v247, s[60:61] offset:2304
	global_atomic_add v246, v247, s[60:61] offset:2560
	global_atomic_add v246, v247, s[60:61] offset:2816
	global_atomic_add v246, v247, s[60:61] offset:3072
	global_atomic_add v246, v247, s[60:61] offset:3328
	global_atomic_add v246, v247, s[60:61] offset:3584
	global_atomic_add v246, v247, s[60:61] offset:3840
	s_branch .Lxb0_done

.LBB0_338:
	s_cmp_lt_i32 s59, 3
	s_barrier
	s_cbranch_scc1 .LBB0_392
	s_waitcnt vmcnt(0)
	s_barrier
	s_and_saveexec_b64 s[2:3], s[0:1]
	s_cbranch_execz .LBB0_391
	s_waitcnt vmcnt(0) lgkmcnt(0)
	v_mov_b32_e32 v241, 0
	v_lshlrev_b32_e64 v254, 8, s31
	v_mov_b32_e32 v247, 1
	v_add_u32_e32 v246, 0x1400, v254
	global_atomic_add v248, v246, v247, s[60:61] sc0
	buffer_inv sc1

.LBB0_587:
	s_cmp_lt_i32 s59, 4
	s_waitcnt vmcnt(0)
	s_barrier
	s_cbranch_scc1 .LBB0_641
	s_waitcnt vmcnt(0)
	s_setprio 0
	s_barrier
	s_and_saveexec_b64 s[2:3], s[0:1]
	s_cbranch_execz .LBB0_640
	s_waitcnt vmcnt(0) lgkmcnt(0)
	v_mov_b32_e32 v241, 0
	v_lshlrev_b32_e64 v254, 8, s31
	v_mov_b32_e32 v247, 1
	v_mov_b32_e32 v246, 0x3600
	global_atomic_add v248, v246, v247, s[60:61] sc0
	buffer_inv sc1

.Lxb2_go:
	v_add_u32_e32 v249, 1, v244
	v_mov_b32_e32 v250, v249
	v_add_u32_e32 v251, 1, v245
	ds_write_b64 v241, v[250:251] offset:8
	v_mul_lo_u32 v251, v251, s56
	v_add_u32_e32 v253, 0x2400, v254
	v_mov_b32_e32 v252, 0
	s_waitcnt vmcnt(0)
	v_add_u32_e32 v248, 1, v248
	v_cmp_eq_u32_e32 vcc, v248, v251
	s_cbranch_vccz .Lxb2_wait
	v_mov_b32_e32 v246, 0x2400
	global_atomic_add v246, v247, s[60:61]
	global_atomic_add v246, v247, s[60:61] offset:256
	global_atomic_add v246, v247, s[60:61] offset:512
	global_atomic_add v246, v247, s[60:61] offset:768
	global_atomic_add v246, v247, s[60:61] offset:1024
	global_atomic_add v246, v247, s[60:61] offset:1280
	global_atomic_add v246, v247, s[60:61] offset:1536
	global_atomic_add v246, v247, s[60:61] offset:1792
	global_atomic_add v246, v247, s[60:61] offset:2048
	global_atomic_add v246, v247, s[60:61] offset:2304
	global_atomic_add v246, v247, s[60:61] offset:2560
	global_atomic_add v246, v247, s[60:61] offset:2816
	global_atomic_add v246, v247, s[60:61] offset:3072
	global_atomic_add v246, v247, s[60:61] offset:3328
	global_atomic_add v246, v247, s[60:61] offset:3584
	global_atomic_add v246, v247, s[60:61] offset:3840
	s_branch .Lxb2_done

.LBB0_657:
	s_cmp_lt_i32 s59, 5
	s_barrier
	s_cbranch_scc1 .LBB0_711
	s_waitcnt vmcnt(0)
	s_barrier
	s_and_saveexec_b64 s[2:3], s[0:1]
	s_cbranch_execz .LBB0_710
	s_waitcnt vmcnt(0) lgkmcnt(0)
	v_mov_b32_e32 v241, 0
	v_lshlrev_b32_e64 v254, 8, s31
	v_mov_b32_e32 v247, 1
	v_add_u32_e32 v246, 0x1400, v254
	global_atomic_add v248, v246, v247, s[60:61] sc0
	buffer_inv sc1

.LBB0_833:
	s_cmp_lt_i32 s59, 6
	s_waitcnt vmcnt(0)
	s_barrier
	s_cbranch_scc1 .LBB0_887
	s_waitcnt vmcnt(0)
	s_barrier
	s_and_saveexec_b64 s[2:3], s[0:1]
	s_cbranch_execz .LBB0_886
	s_waitcnt vmcnt(0) lgkmcnt(0)
	v_mov_b32_e32 v241, 0
	v_lshlrev_b32_e64 v254, 8, s31
	v_mov_b32_e32 v247, 1
	v_mov_b32_e32 v246, 0x3600
	global_atomic_add v248, v246, v247, s[60:61] sc0
	buffer_inv sc1

.LBB0_986:
	s_cmp_lt_i32 s59, 7
	s_barrier
	s_cbranch_scc1 .LBB0_1040
	s_waitcnt vmcnt(0)
	s_barrier
	s_and_saveexec_b64 s[2:3], s[0:1]
	s_cbranch_execz .LBB0_1039
	s_waitcnt vmcnt(0) lgkmcnt(0)
	v_mov_b32_e32 v241, 0
	v_lshlrev_b32_e64 v254, 8, s31
	v_mov_b32_e32 v247, 1
	v_add_u32_e32 v246, 0x1400, v254
	global_atomic_add v248, v246, v247, s[60:61] sc0
	buffer_inv sc1

.LBB0_1106:
	s_cmp_lt_i32 s59, 8
	s_barrier
	s_cbranch_scc1 .LBB0_1160
	s_waitcnt vmcnt(0)
	s_barrier
	s_and_saveexec_b64 s[2:3], s[0:1]
	s_cbranch_execz .LBB0_1159
	s_waitcnt vmcnt(0) lgkmcnt(0)
	v_mov_b32_e32 v241, 0
	v_lshlrev_b32_e64 v254, 8, s31
	v_mov_b32_e32 v247, 1
	v_add_u32_e32 v246, 0x1400, v254
	global_atomic_add v248, v246, v247, s[60:61] sc0
	buffer_inv sc1

.LBB0_1285:
	s_cmp_lt_i32 s59, 10
	s_waitcnt vmcnt(0)
	s_barrier
	s_cbranch_scc1 .LBB0_1339
	s_waitcnt vmcnt(0)
	s_setprio 0
	s_barrier
	s_and_saveexec_b64 s[2:3], s[0:1]
	s_cbranch_execz .LBB0_1338
	s_waitcnt vmcnt(0) lgkmcnt(0)
	v_mov_b32_e32 v241, 0
	v_lshlrev_b32_e64 v254, 8, s31
	v_mov_b32_e32 v247, 1
	v_mov_b32_e32 v246, 0x3600
	global_atomic_add v248, v246, v247, s[60:61] sc0
	buffer_inv sc1

.LBB0_1347:
	s_cmp_lt_i32 s59, 11
	s_barrier
	s_cbranch_scc1 .LBB0_1401
	s_waitcnt vmcnt(0)
	s_barrier
	s_and_saveexec_b64 s[2:3], s[0:1]
	s_cbranch_execz .LBB0_1400
	s_waitcnt vmcnt(0) lgkmcnt(0)
	v_mov_b32_e32 v241, 0
	v_lshlrev_b32_e64 v254, 8, s31
	v_mov_b32_e32 v247, 1
	v_add_u32_e32 v246, 0x1400, v254
	global_atomic_add v248, v246, v247, s[60:61] sc0
	buffer_inv sc1

.Lcv4_2:
.LBB0_1558:
	s_cmp_lt_i32 s59, 12
	s_waitcnt lgkmcnt(0)
	s_barrier
	s_cbranch_scc1 .LBB0_1612
	s_waitcnt vmcnt(0)
	s_setprio 0
	s_barrier
	s_and_saveexec_b64 s[2:3], s[0:1]
	s_cbranch_execz .LBB0_1611
	s_waitcnt vmcnt(0) lgkmcnt(0)
	v_mov_b32_e32 v241, 0
	v_lshlrev_b32_e64 v254, 8, s31
	v_mov_b32_e32 v247, 1
	v_mov_b32_e32 v246, 0x3600
	global_atomic_add v248, v246, v247, s[60:61] sc0
	buffer_inv sc1

.LBB0_2400:
	s_cmp_lt_i32 s59, 14
	s_waitcnt vmcnt(0)
	s_barrier
	s_cbranch_scc1 .LBB0_2454
	s_waitcnt vmcnt(0)
	s_setprio 0
	s_barrier
	s_and_saveexec_b64 s[2:3], s[0:1]
	s_cbranch_execz .LBB0_2453
	s_waitcnt vmcnt(0) lgkmcnt(0)
	v_mov_b32_e32 v241, 0
	v_lshlrev_b32_e64 v254, 8, s31
	v_mov_b32_e32 v247, 1
	v_mov_b32_e32 v246, 0x3600
	global_atomic_add v248, v246, v247, s[60:61] sc0
	buffer_inv sc1

.LBB0_2462:
	s_cmp_lt_i32 s59, 15
	s_barrier
	s_cbranch_scc1 .LBB0_2516
	s_waitcnt vmcnt(0)
	s_barrier
	s_and_saveexec_b64 s[2:3], s[0:1]
	s_cbranch_execz .LBB0_2515
	s_waitcnt vmcnt(0) lgkmcnt(0)
	v_mov_b32_e32 v241, 0
	v_lshlrev_b32_e64 v254, 8, s31
	v_mov_b32_e32 v247, 1
	v_add_u32_e32 v246, 0x1400, v254
	global_atomic_add v248, v246, v247, s[60:61] sc0
	buffer_inv sc1

.LBB0_2579:
	s_cmp_lt_i32 s59, 16
	s_waitcnt vmcnt(0)
	s_barrier
	s_cbranch_scc1 .LBB0_2634
	s_waitcnt vmcnt(0)
	s_setprio 0
	s_barrier
	s_and_saveexec_b64 s[2:3], s[0:1]
	s_cbranch_execz .LBB0_2633
	s_waitcnt vmcnt(0) lgkmcnt(0)
	v_mov_b32_e32 v241, 0
	v_lshlrev_b32_e64 v254, 8, s31
	v_mov_b32_e32 v247, 1
	v_mov_b32_e32 v246, 0x3600
	global_atomic_add v248, v246, v247, s[60:61] sc0
	buffer_inv sc1

.LBB0_2702:
	s_cmp_lt_i32 s59, 17
	s_barrier
	s_cbranch_scc1 .LBB0_2756
	s_waitcnt vmcnt(0)
	s_barrier
	s_and_saveexec_b64 s[2:3], s[0:1]
	s_cbranch_execz .LBB0_2755
	s_waitcnt vmcnt(0) lgkmcnt(0)
	v_mov_b32_e32 v241, 0
	v_lshlrev_b32_e64 v254, 8, s31
	v_mov_b32_e32 v247, 1
	v_add_u32_e32 v246, 0x1400, v254
	global_atomic_add v248, v246, v247, s[60:61] sc0
	buffer_inv sc1

.LBB0_2844:
	s_cmp_lt_i32 s59, 18
	s_barrier
	s_cbranch_scc1 .LBB0_2898
	s_waitcnt vmcnt(0)
	s_barrier
	s_and_saveexec_b64 s[2:3], s[0:1]
	s_cbranch_execz .LBB0_2897
	s_waitcnt vmcnt(0) lgkmcnt(0)
	v_mov_b32_e32 v241, 0
	v_lshlrev_b32_e64 v254, 8, s31
	v_mov_b32_e32 v247, 1
	v_add_u32_e32 v246, 0x1400, v254
	global_atomic_add v248, v246, v247, s[60:61] sc0
	buffer_inv sc1

.LBB0_3024:
	s_cmp_lt_i32 s59, 20
	s_waitcnt vmcnt(0)
	s_barrier
	s_cbranch_scc1 .LBB0_3078
	s_waitcnt vmcnt(0)
	s_barrier
	s_and_saveexec_b64 s[2:3], s[0:1]
	s_cbranch_execz .LBB0_3077
	s_waitcnt vmcnt(0) lgkmcnt(0)
	v_mov_b32_e32 v241, 0
	v_lshlrev_b32_e64 v254, 8, s31
	v_mov_b32_e32 v247, 1
	v_add_u32_e32 v246, 0x1400, v254
	global_atomic_add v248, v246, v247, s[60:61] sc0
	buffer_inv sc1

.LBB0_3082:
	s_cmp_lt_u32 s59, 21
	s_barrier
	s_cbranch_scc1 .LBB0_3136
	s_waitcnt vmcnt(0)
	s_barrier
	s_and_saveexec_b64 s[2:3], s[0:1]
	s_cbranch_execz .LBB0_3135
	s_waitcnt vmcnt(0) lgkmcnt(0)
	v_mov_b32_e32 v241, 0
	v_lshlrev_b32_e64 v254, 8, s31
	v_mov_b32_e32 v247, 1
	v_mov_b32_e32 v246, 0x3600
	global_atomic_add v248, v246, v247, s[60:61] sc0
	buffer_inv sc1

.LBB0_3155:
	s_cmp_lt_i32 s59, 22
	s_waitcnt vmcnt(0)
	s_barrier
	s_cbranch_scc1 .LBB0_3209
	s_waitcnt vmcnt(0)
	s_setprio 0
	s_barrier
	s_and_saveexec_b64 s[2:3], s[0:1]
	s_cbranch_execz .LBB0_3208
	s_waitcnt vmcnt(0) lgkmcnt(0)
	v_mov_b32_e32 v241, 0
	v_lshlrev_b32_e64 v254, 8, s31
	v_mov_b32_e32 v247, 1
	v_mov_b32_e32 v246, 0x3600
	global_atomic_add v248, v246, v247, s[60:61] sc0
	buffer_inv sc1

.LBB0_3217:
	s_cmp_lt_i32 s59, 23
	s_barrier
	s_cbranch_scc1 .LBB0_3271
	s_waitcnt vmcnt(0)
	s_barrier
	s_and_saveexec_b64 s[2:3], s[0:1]
	s_cbranch_execz .LBB0_3270
	s_waitcnt vmcnt(0) lgkmcnt(0)
	v_mov_b32_e32 v241, 0
	v_lshlrev_b32_e64 v254, 8, s31
	v_mov_b32_e32 v247, 1
	v_add_u32_e32 v246, 0x1400, v254
	global_atomic_add v248, v246, v247, s[60:61] sc0
	buffer_inv sc1

.LBB0_3341:
	s_cmp_lt_i32 s59, 24
	s_waitcnt lgkmcnt(0)
	s_barrier
	s_cbranch_scc1 .LBB0_3395
	s_waitcnt vmcnt(0)
	s_setprio 0
	s_barrier
	s_and_saveexec_b64 s[2:3], s[0:1]
	s_cbranch_execz .LBB0_3394
	s_waitcnt vmcnt(0) lgkmcnt(0)
	v_mov_b32_e32 v241, 0
	v_lshlrev_b32_e64 v254, 8, s31
	v_mov_b32_e32 v247, 1
	v_mov_b32_e32 v246, 0x3600
	global_atomic_add v248, v246, v247, s[60:61] sc0
	buffer_inv sc1

.LBB0_3517:
	s_cmp_lt_i32 s59, 26
	s_waitcnt vmcnt(0)
	s_barrier
	s_cbranch_scc1 .LBB0_3571
	s_waitcnt vmcnt(0)
	s_setprio 0
	s_barrier
	s_and_saveexec_b64 s[2:3], s[0:1]
	s_cbranch_execz .LBB0_3570
	s_waitcnt vmcnt(0) lgkmcnt(0)
	v_mov_b32_e32 v241, 0
	v_lshlrev_b32_e64 v254, 8, s31
	v_mov_b32_e32 v247, 1
	v_mov_b32_e32 v246, 0x3600
	global_atomic_add v248, v246, v247, s[60:61] sc0
	buffer_inv sc1
